# attention: long-lead LDS fragment reads (V prefetch in softmax phase, K frags issued 8 MFMAs ahead)
# speedup vs baseline: 1.0399x; 1.0177x over previous
; DI void diff_core(unsigned char* smem, const u16* qptr, const u16* kbase, const u16* vtbase, int vld,
;                   int ntb, int ntw, int nvalid, int ks0, const float* lut, int qpos, bool active, bool grpB,
;                   f32x16 (&O)[4], float& l_out) {
;     ...
;     float mx = S[0][0];
; #pragma unroll
;     for (int kb = 0; kb < 2; ++kb)
; #pragma unroll
;       for (int i = 0; i < 16; ++i) mx = fmaxf(mx, S[kb][i]);
;     {
;       const unsigned um = __float_as_uint(mx);
;       const auto sw = __builtin_amdgcn_permlane32_swap(um, um, false, false);
;       mx = fmaxf(__uint_as_float(sw[0]), __uint_as_float(sw[1]));
;     }
;     if (t == 0) {
;       m = mx;
; #pragma unroll
;       for (int kb = 0; kb < 2; ++kb)
; #pragma unroll
;         for (int i = 0; i < 16; ++i) S[kb][i] -= mx;
;     } else if (__any(mx > 8.f)) {
;       const float d = fmaxf(mx, 0.f);
;       const float alpha = __builtin_amdgcn_exp2f(-d);
;       m += d;
;       l *= alpha;
; #pragma unroll
;       for (int tt = 0; tt < 4; ++tt)
; #pragma unroll
;         for (int e = 0; e < 16; ++e) O[tt][e] *= alpha;
; #pragma unroll
;       for (int kb = 0; kb < 2; ++kb)
; #pragma unroll
;         for (int i = 0; i < 16; ++i) S[kb][i] -= d;
;     }
;     float ps = 0.f;
; #pragma unroll
;     for (int kb = 0; kb < 2; ++kb)
; #pragma unroll
;       for (int i = 0; i < 16; ++i) {
;         const float pe = __builtin_amdgcn_exp2f(S[kb][i]);
;         S[kb][i] = pe;
;         ps += pe;
;       }
;     l += ps;
.LBB0_357:
	v_max_f32_e32 v32, v1, v1
	v_max_f32_e32 v33, v0, v0
	v_max_f32_e32 v32, v33, v32
	v_max3_f32 v32, v32, v2, v3
	v_max3_f32 v32, v32, v4, v5
	v_max3_f32 v32, v32, v6, v7
	v_max3_f32 v32, v32, v8, v9
	v_max3_f32 v32, v32, v10, v11
	v_max3_f32 v32, v32, v12, v13
	v_max3_f32 v32, v32, v14, v15
	v_max3_f32 v32, v32, v16, v17
	v_max3_f32 v32, v32, v18, v19
	v_max3_f32 v32, v32, v20, v21
	v_max3_f32 v32, v32, v22, v23
	v_max3_f32 v32, v32, v24, v25
	v_max3_f32 v32, v32, v26, v27
	v_max3_f32 v32, v32, v28, v29
	v_max3_f32 v32, v32, v30, v31
	v_mov_b32_e32 v33, v32
	s_nop 1
	v_permlane32_swap_b32_e32 v32, v33
	v_max_f32_e32 v33, v33, v33
	v_max_f32_e32 v32, v32, v32
	v_max_f32_e32 v191, v32, v33
	v_xor_b32_e32 v232, 0x80000000, v191
	v_mov_b32_e32 v233, v232
	v_mov_b32_e32 v234, v232
	v_mov_b32_e32 v235, v232
	v_mov_b32_e32 v236, v232
	v_mov_b32_e32 v237, v232
	v_mov_b32_e32 v238, v232
	v_mov_b32_e32 v239, v232
	v_mov_b32_e32 v240, v232
	v_mov_b32_e32 v241, v232
	v_mov_b32_e32 v242, v232
	v_mov_b32_e32 v243, v232
	v_mov_b32_e32 v244, v232
	v_mov_b32_e32 v245, v232
	v_mov_b32_e32 v246, v232
	v_mov_b32_e32 v247, v232
	v_sub_f32_e32 v0, v0, v191
	v_sub_f32_e32 v1, v1, v191
	v_exp_f32_e32 v96, v0
	v_sub_f32_e32 v2, v2, v191
	v_exp_f32_e32 v97, v1
	v_sub_f32_e32 v3, v3, v191
	v_exp_f32_e32 v98, v2
	v_sub_f32_e32 v4, v4, v191
	v_exp_f32_e32 v99, v3
	v_sub_f32_e32 v5, v5, v191
	v_exp_f32_e32 v100, v4
	v_sub_f32_e32 v6, v6, v191
	v_exp_f32_e32 v101, v5
	v_sub_f32_e32 v7, v7, v191
	v_exp_f32_e32 v102, v6
	v_sub_f32_e32 v8, v8, v191
	v_exp_f32_e32 v103, v7
	v_sub_f32_e32 v9, v9, v191
	v_exp_f32_e32 v104, v8
	v_sub_f32_e32 v10, v10, v191
	v_exp_f32_e32 v105, v9
	v_sub_f32_e32 v11, v11, v191
	v_exp_f32_e32 v106, v10
	v_sub_f32_e32 v12, v12, v191
	v_exp_f32_e32 v107, v11
	v_sub_f32_e32 v13, v13, v191
	v_exp_f32_e32 v108, v12
	v_sub_f32_e32 v14, v14, v191
	v_exp_f32_e32 v109, v13
	v_sub_f32_e32 v15, v15, v191
	v_exp_f32_e32 v110, v14
	v_sub_f32_e32 v16, v16, v191
	v_exp_f32_e32 v111, v15
	v_sub_f32_e32 v17, v17, v191
	v_exp_f32_e32 v112, v16
	v_sub_f32_e32 v18, v18, v191
	v_exp_f32_e32 v113, v17
	v_sub_f32_e32 v19, v19, v191
	v_exp_f32_e32 v114, v18
	v_sub_f32_e32 v20, v20, v191
	v_exp_f32_e32 v115, v19
	v_sub_f32_e32 v21, v21, v191
	v_exp_f32_e32 v116, v20
	v_sub_f32_e32 v22, v22, v191
	v_exp_f32_e32 v117, v21
	v_sub_f32_e32 v23, v23, v191
	v_exp_f32_e32 v118, v22
	v_sub_f32_e32 v24, v24, v191
	v_exp_f32_e32 v119, v23
	v_sub_f32_e32 v25, v25, v191
	v_exp_f32_e32 v120, v24
	v_sub_f32_e32 v26, v26, v191
	v_exp_f32_e32 v121, v25
	v_sub_f32_e32 v27, v27, v191
	v_exp_f32_e32 v122, v26
	v_sub_f32_e32 v28, v28, v191
	v_exp_f32_e32 v123, v27
	v_sub_f32_e32 v29, v29, v191
	v_exp_f32_e32 v124, v28
	v_sub_f32_e32 v30, v30, v191
	v_exp_f32_e32 v125, v29
	v_sub_f32_e32 v31, v31, v191
	v_exp_f32_e32 v126, v30
	v_exp_f32_e32 v127, v31
	s_lshl_b32 s0, s62, 1
	s_sub_i32 s63, 0, s0
	s_lshl_b32 s0, s59, 10
	s_lshl_b32 s1, s62, 9
	s_add_i32 s0, s0, s1
	v_mov_b32_e32 v181, 0
	v_or_b32_e32 v0, s0, v183
	v_lshlrev_b32_e32 v1, 2, v182
	v_sub_u32_e32 v0, v0, v1
	s_lshl_b32 s0, s39, 7
	v_subrev_u32_e32 v0, s0, v0
	v_mov_b32_e32 v14, v163
	v_mov_b32_e32 v15, v163
	v_add_u32_e32 v199, s38, v0
	v_mov_b32_e32 v0, v163
	v_mov_b32_e32 v1, v163
	v_mov_b32_e32 v2, v163
	v_mov_b32_e32 v3, v163
	v_mov_b32_e32 v4, v163
	v_mov_b32_e32 v5, v163
	v_mov_b32_e32 v6, v163
	v_mov_b32_e32 v7, v163
	v_mov_b32_e32 v8, v163
	v_mov_b32_e32 v9, v163
	v_mov_b32_e32 v10, v163
	v_mov_b32_e32 v11, v163
	v_mov_b32_e32 v12, v163
	v_mov_b32_e32 v13, v163
	v_mov_b64_e32 v[30:31], v[14:15]
	v_mov_b64_e32 v[46:47], v[14:15]
	v_mov_b64_e32 v[62:63], v[14:15]
	v_add_u32_e32 v195, v188, v184
	v_add_u32_e32 v196, v187, v184
	v_add_u32_e32 v197, v186, v184
	v_add_u32_e32 v198, v185, v184
	s_movk_i32 s64, 0xff00
	s_mov_b32 s65, 0x20000
	v_mov_b64_e32 v[28:29], v[12:13]
	v_mov_b64_e32 v[26:27], v[10:11]
	v_mov_b64_e32 v[24:25], v[8:9]
	v_mov_b64_e32 v[22:23], v[6:7]
	v_mov_b64_e32 v[20:21], v[4:5]
	v_mov_b64_e32 v[18:19], v[2:3]
	v_mov_b64_e32 v[16:17], v[0:1]
	v_mov_b64_e32 v[44:45], v[12:13]
	v_mov_b64_e32 v[42:43], v[10:11]
	v_mov_b64_e32 v[40:41], v[8:9]
	v_mov_b64_e32 v[38:39], v[6:7]
	v_mov_b64_e32 v[36:37], v[4:5]
	v_mov_b64_e32 v[34:35], v[2:3]
	v_mov_b64_e32 v[32:33], v[0:1]
	v_mov_b64_e32 v[60:61], v[12:13]
	v_mov_b64_e32 v[58:59], v[10:11]
	v_mov_b64_e32 v[56:57], v[8:9]
	v_mov_b64_e32 v[54:55], v[6:7]
	v_mov_b64_e32 v[52:53], v[4:5]
	v_mov_b64_e32 v[50:51], v[2:3]
	v_mov_b64_e32 v[48:49], v[0:1]
	s_mov_b32 s0, 0
	v_add_u32_e32 v248, s0, v195
	ds_read_b128 v[200:203], v248 offset:16384
	ds_read_b128 v[204:207], v248 offset:20480
	ds_read_b128 v[208:211], v248 offset:24576
	ds_read_b128 v[212:215], v248 offset:28672
	v_add_u32_e32 v249, s0, v196
	ds_read_b128 v[216:219], v249 offset:16384
	ds_read_b128 v[220:223], v249 offset:20480
	ds_read_b128 v[224:227], v249 offset:24576
	ds_read_b128 v[228:231], v249 offset:28672
	s_branch .LBB0_360
.LBB0_358:
	v_exp_f32_e32 v96, v96
	v_exp_f32_e32 v97, v97
	v_exp_f32_e32 v98, v98
	v_exp_f32_e32 v99, v99
	v_exp_f32_e32 v100, v100
	v_exp_f32_e32 v101, v101
	v_exp_f32_e32 v102, v102
	v_exp_f32_e32 v103, v103
	v_exp_f32_e32 v104, v104
	v_exp_f32_e32 v105, v105
	v_exp_f32_e32 v106, v106
	v_exp_f32_e32 v107, v107
	v_exp_f32_e32 v108, v108
	v_exp_f32_e32 v109, v109
	v_exp_f32_e32 v110, v110
	v_exp_f32_e32 v111, v111
	v_exp_f32_e32 v112, v112
	v_exp_f32_e32 v113, v113
	v_exp_f32_e32 v114, v114
	v_exp_f32_e32 v115, v115
	v_exp_f32_e32 v116, v116
	v_exp_f32_e32 v117, v117
	v_exp_f32_e32 v118, v118
	v_exp_f32_e32 v119, v119
	v_exp_f32_e32 v120, v120
	v_exp_f32_e32 v121, v121
	v_exp_f32_e32 v122, v122
	v_exp_f32_e32 v123, v123
	v_exp_f32_e32 v124, v124
	v_exp_f32_e32 v125, v125
	v_exp_f32_e32 v126, v126
	v_exp_f32_e32 v127, v127
	s_add_i32 s0, s65, 0x8000
	s_and_b32 s0, s0, 0x18000
	v_add_u32_e32 v248, s0, v195
	ds_read_b128 v[200:203], v248 offset:16384
	ds_read_b128 v[204:207], v248 offset:20480
	ds_read_b128 v[208:211], v248 offset:24576
	ds_read_b128 v[212:215], v248 offset:28672
	v_add_u32_e32 v249, s0, v196
	ds_read_b128 v[216:219], v249 offset:16384
	ds_read_b128 v[220:223], v249 offset:20480
	ds_read_b128 v[224:227], v249 offset:24576
	ds_read_b128 v[228:231], v249 offset:28672

; #define LAS __attribute__((address_space(3)))
; DI void diff_core(unsigned char* smem, const u16* qptr, const u16* kbase, const u16* vtbase, int vld,
;                   int ntb, int ntw, int nvalid, int ks0, const float* lut, int qpos, bool active, bool grpB,
;                   f32x16 (&O)[4], float& l_out) {
;     ...
;     for (int s = 0; s < 4; ++s)
; #pragma unroll
;       for (int kb = 0; kb < 2; ++kb) kf[s][kb] = *reinterpret_cast<const LAS bf16x8*>(b + koff[s] + kb * 32 * 256);
; #pragma unroll
;     for (int s = 0; s < 4; ++s)
; #pragma unroll
;       for (int kb = 0; kb < 2; ++kb) S[kb] = MFMA(kf[s][kb], qf[s], S[kb]);
;     ...
;   auto pv = [&](int slot) {
;     if (grpB) __builtin_amdgcn_s_setprio(2); else __builtin_amdgcn_s_setprio(1);
;     const LAS unsigned char* b = lds + slot * D_SLOT;
;     bf16x8 va[4], vb[4];
; #pragma unroll
;     for (int tt = 0; tt < 4; ++tt) va[tt] = *reinterpret_cast<const LAS bf16x8*>(b + voff[0] + tt * 32 * 128);
; #pragma unroll
;     for (int tt = 0; tt < 4; ++tt) vb[tt] = *reinterpret_cast<const LAS bf16x8*>(b + voff[1] + tt * 32 * 128);
;     {
;       const bf16x8 pf = __builtin_bit_cast(bf16x8, P[0]);
; #pragma unroll
;       for (int tt = 0; tt < 4; ++tt) O[tt] = MFMA(va[tt], pf, O[tt]);
;     }
; #pragma unroll
;     for (int tt = 0; tt < 4; ++tt) va[tt] = *reinterpret_cast<const LAS bf16x8*>(b + voff[2] + tt * 32 * 128);
;     {
;       const bf16x8 pf = __builtin_bit_cast(bf16x8, P[1]);
; #pragma unroll
;       for (int tt = 0; tt < 4; ++tt) O[tt] = MFMA(vb[tt], pf, O[tt]);
;     }
; #pragma unroll
;     for (int tt = 0; tt < 4; ++tt) vb[tt] = *reinterpret_cast<const LAS bf16x8*>(b + voff[3] + tt * 32 * 128);
;     {
;       const bf16x8 pf = __builtin_bit_cast(bf16x8, P[2]);
; #pragma unroll
;       for (int tt = 0; tt < 4; ++tt) O[tt] = MFMA(va[tt], pf, O[tt]);
;     }
;     {
;       const bf16x8 pf = __builtin_bit_cast(bf16x8, P[3]);
; #pragma unroll
;       for (int tt = 0; tt < 4; ++tt) O[tt] = MFMA(vb[tt], pf, O[tt]);
;     }
;     __builtin_amdgcn_sched_group_barrier(0x100, 8, 0);
;     __builtin_amdgcn_sched_group_barrier(0x008, 4, 0);
;     __builtin_amdgcn_sched_group_barrier(0x100, 4, 0);
;     __builtin_amdgcn_sched_group_barrier(0x008, 4, 0);
;     __builtin_amdgcn_sched_group_barrier(0x100, 4, 0);
;     __builtin_amdgcn_sched_group_barrier(0x008, 8, 0);
;     __builtin_amdgcn_s_setprio(0);
;   };
.LBB0_360:
	s_add_i32 s66, s64, 0x101
	s_cmp_gt_u32 s66, s16
	s_cbranch_scc1 .LBB0_362
	s_setprio 1
	s_and_b32 s0, s65, 0x18000
	v_add_u32_e32 v248, s0, v197
	ds_read_b128 v[64:67], v248 offset:16384
	ds_read_b128 v[68:71], v248 offset:20480
	ds_read_b128 v[72:75], v248 offset:24576
	ds_read_b128 v[76:79], v248 offset:28672
	s_add_i32 s67, s65, 0xfffe8000
	s_and_b32 s67, s67, 0x18000
	v_cvt_pk_bf16_f32 v144, v96, v97
	v_cvt_pk_bf16_f32 v145, v98, v99
	v_cvt_pk_bf16_f32 v146, v100, v101
	v_cvt_pk_bf16_f32 v147, v102, v103
	v_add_f32_e32 v250, v97, v96
	v_add_f32_e32 v250, v98, v250
	s_waitcnt lgkmcnt(4)
	v_mfma_f32_32x32x16_bf16 v[48:63], v[200:203], v[144:147], v[48:63]
	v_cvt_pk_bf16_f32 v148, v104, v105
	v_add_f32_e32 v250, v99, v250
	v_add_f32_e32 v250, v100, v250
	v_add_u32_e32 v249, s0, v198
	ds_read_b128 v[80:83], v249 offset:16384
	ds_read_b128 v[84:87], v249 offset:20480
	ds_read_b128 v[88:91], v249 offset:24576
	ds_read_b128 v[92:95], v249 offset:28672
	v_mfma_f32_32x32x16_bf16 v[32:47], v[204:207], v[144:147], v[32:47]
	v_cvt_pk_bf16_f32 v149, v106, v107
	v_add_f32_e32 v250, v101, v250
	v_add_f32_e32 v250, v102, v250
	v_mfma_f32_32x32x16_bf16 v[16:31], v[208:211], v[144:147], v[16:31]
	v_cvt_pk_bf16_f32 v150, v108, v109
	v_add_f32_e32 v250, v103, v250
	v_add_f32_e32 v250, v104, v250
	v_mfma_f32_32x32x16_bf16 v[0:15], v[212:215], v[144:147], v[0:15]
	v_cvt_pk_bf16_f32 v151, v110, v111
	v_add_f32_e32 v250, v105, v250
	v_add_f32_e32 v250, v106, v250
	v_mfma_f32_32x32x16_bf16 v[48:63], v[216:219], v[148:151], v[48:63]
	v_cvt_pk_bf16_f32 v152, v112, v113
	v_add_f32_e32 v250, v107, v250
	v_add_f32_e32 v250, v108, v250
	v_mfma_f32_32x32x16_bf16 v[32:47], v[220:223], v[148:151], v[32:47]
	v_cvt_pk_bf16_f32 v153, v114, v115
	v_add_f32_e32 v250, v109, v250
	v_add_f32_e32 v250, v110, v250
	v_mfma_f32_32x32x16_bf16 v[16:31], v[224:227], v[148:151], v[16:31]
	v_cvt_pk_bf16_f32 v154, v116, v117
	v_add_f32_e32 v250, v111, v250
	v_add_f32_e32 v250, v112, v250
	v_mfma_f32_32x32x16_bf16 v[0:15], v[228:231], v[148:151], v[0:15]
	v_cvt_pk_bf16_f32 v155, v118, v119
	v_add_f32_e32 v250, v113, v250
	v_add_f32_e32 v250, v114, v250
	v_add_u32_e32 v248, s67, v177
	ds_read_b128 v[200:203], v248
	ds_read_b128 v[204:207], v248 offset:8192
	v_add_u32_e32 v249, s67, v178
	ds_read_b128 v[208:211], v249
	ds_read_b128 v[212:215], v249 offset:8192
	s_waitcnt lgkmcnt(8)
	v_mfma_f32_32x32x16_bf16 v[48:63], v[64:67], v[152:155], v[48:63]
	v_cvt_pk_bf16_f32 v156, v120, v121
	v_add_f32_e32 v250, v115, v250
	v_add_f32_e32 v250, v116, v250
	v_mfma_f32_32x32x16_bf16 v[32:47], v[68:71], v[152:155], v[32:47]
	v_cvt_pk_bf16_f32 v157, v122, v123
	v_add_f32_e32 v250, v117, v250
	v_add_f32_e32 v250, v118, v250
	v_mfma_f32_32x32x16_bf16 v[16:31], v[72:75], v[152:155], v[16:31]
	v_cvt_pk_bf16_f32 v158, v124, v125
	v_add_f32_e32 v250, v119, v250
	v_add_f32_e32 v250, v120, v250
	v_mfma_f32_32x32x16_bf16 v[0:15], v[76:79], v[152:155], v[0:15]
	v_cvt_pk_bf16_f32 v159, v126, v127
	v_add_f32_e32 v250, v121, v250
	v_add_f32_e32 v250, v122, v250
	v_add_u32_e32 v248, s67, v179
	ds_read_b128 v[216:219], v248
	ds_read_b128 v[220:223], v248 offset:8192
	v_add_u32_e32 v249, s67, v180
	ds_read_b128 v[224:227], v249
	ds_read_b128 v[228:231], v249 offset:8192
	s_waitcnt lgkmcnt(8)
	v_mfma_f32_32x32x16_bf16 v[48:63], v[80:83], v[156:159], v[48:63]
	v_add_f32_e32 v250, v123, v250
	v_add_f32_e32 v250, v124, v250
	v_mfma_f32_32x32x16_bf16 v[32:47], v[84:87], v[156:159], v[32:47]
	v_add_f32_e32 v250, v125, v250
	v_add_f32_e32 v250, v126, v250
	v_mfma_f32_32x32x16_bf16 v[16:31], v[88:91], v[156:159], v[16:31]
	v_add_f32_e32 v250, v127, v250
	v_mfma_f32_32x32x16_bf16 v[0:15], v[92:95], v[156:159], v[0:15]
	v_add_f32_e32 v181, v181, v250
	s_setprio 0
.LBB0_362:
	s_cmp_lt_u32 s66, s16
	s_cselect_b64 s[0:1], -1, 0
	s_cmp_ge_u32 s66, s16
	s_cbranch_scc1 .LBB0_364
	s_setprio 1
	s_waitcnt lgkmcnt(0)
	v_mfma_f32_32x32x16_bf16 v[96:111], v[200:203], v[128:131], v[232:247]
	v_mfma_f32_32x32x16_bf16 v[112:127], v[204:207], v[128:131], v[232:247]
	v_mfma_f32_32x32x16_bf16 v[96:111], v[208:211], v[132:135], v[96:111]
	v_mfma_f32_32x32x16_bf16 v[112:127], v[212:215], v[132:135], v[112:127]
	v_mfma_f32_32x32x16_bf16 v[96:111], v[216:219], v[136:139], v[96:111]
	v_mfma_f32_32x32x16_bf16 v[112:127], v[220:223], v[136:139], v[112:127]
	v_mfma_f32_32x32x16_bf16 v[96:111], v[224:227], v[140:143], v[96:111]
	v_mfma_f32_32x32x16_bf16 v[112:127], v[228:231], v[140:143], v[112:127]
	s_setprio 0

; #define MFMA(a, b, c) __builtin_amdgcn_mfma_f32_32x32x16_bf16((a), (b), (c), 0, 0, 0)
; DI void diff_core(unsigned char* smem, const u16* qptr, const u16* kbase, const u16* vtbase, int vld,
;                   int ntb, int ntw, int nvalid, int ks0, const float* lut, int qpos, bool active, bool grpB,
;                   f32x16 (&O)[4], float& l_out) {
;     ...
;   auto pv = [&](int slot) {
;     if (grpB) __builtin_amdgcn_s_setprio(2); else __builtin_amdgcn_s_setprio(1);
;     const LAS unsigned char* b = lds + slot * D_SLOT;
;     bf16x8 va[4], vb[4];
; #pragma unroll
;     for (int tt = 0; tt < 4; ++tt) va[tt] = *reinterpret_cast<const LAS bf16x8*>(b + voff[0] + tt * 32 * 128);
; #pragma unroll
;     for (int tt = 0; tt < 4; ++tt) vb[tt] = *reinterpret_cast<const LAS bf16x8*>(b + voff[1] + tt * 32 * 128);
;     {
;       const bf16x8 pf = __builtin_bit_cast(bf16x8, P[0]);
; #pragma unroll
;       for (int tt = 0; tt < 4; ++tt) O[tt] = MFMA(va[tt], pf, O[tt]);
;     }
; #pragma unroll
;     for (int tt = 0; tt < 4; ++tt) va[tt] = *reinterpret_cast<const LAS bf16x8*>(b + voff[2] + tt * 32 * 128);
;     {
;       const bf16x8 pf = __builtin_bit_cast(bf16x8, P[1]);
; #pragma unroll
;       for (int tt = 0; tt < 4; ++tt) O[tt] = MFMA(vb[tt], pf, O[tt]);
;     }
; #pragma unroll
;     for (int tt = 0; tt < 4; ++tt) vb[tt] = *reinterpret_cast<const LAS bf16x8*>(b + voff[3] + tt * 32 * 128);
;     {
;       const bf16x8 pf = __builtin_bit_cast(bf16x8, P[2]);
; #pragma unroll
;       for (int tt = 0; tt < 4; ++tt) O[tt] = MFMA(va[tt], pf, O[tt]);
;     }
;     {
;       const bf16x8 pf = __builtin_bit_cast(bf16x8, P[3]);
; #pragma unroll
;       for (int tt = 0; tt < 4; ++tt) O[tt] = MFMA(vb[tt], pf, O[tt]);
;     }
;     __builtin_amdgcn_sched_group_barrier(0x100, 8, 0);
;     __builtin_amdgcn_sched_group_barrier(0x008, 4, 0);
;     __builtin_amdgcn_sched_group_barrier(0x100, 4, 0);
;     __builtin_amdgcn_sched_group_barrier(0x008, 4, 0);
;     __builtin_amdgcn_sched_group_barrier(0x100, 4, 0);
;     __builtin_amdgcn_sched_group_barrier(0x008, 8, 0);
;     __builtin_amdgcn_s_setprio(0);
;   };
;     ...
;     float ps = 0.f;
; #pragma unroll
;     for (int kb = 0; kb < 2; ++kb)
; #pragma unroll
;       for (int i = 0; i < 16; ++i) {
;         const float pe = __builtin_amdgcn_exp2f(S[kb][i]);
;         S[kb][i] = pe;
;         ps += pe;
;       }
;     l += ps;
.LBB0_383:
	v_exp_f32_e32 v80, v80
	v_exp_f32_e32 v81, v81
	v_exp_f32_e32 v82, v82
	v_exp_f32_e32 v83, v83
	v_exp_f32_e32 v84, v84
	v_exp_f32_e32 v85, v85
	v_exp_f32_e32 v86, v86
	v_exp_f32_e32 v87, v87
	v_exp_f32_e32 v88, v88
	v_exp_f32_e32 v89, v89
	v_exp_f32_e32 v90, v90
	v_exp_f32_e32 v91, v91
	v_exp_f32_e32 v92, v92
	v_exp_f32_e32 v93, v93
	v_exp_f32_e32 v94, v94
	v_exp_f32_e32 v95, v95
	v_exp_f32_e32 v64, v64
	v_exp_f32_e32 v65, v65
	v_exp_f32_e32 v66, v66
	v_exp_f32_e32 v67, v67
	v_exp_f32_e32 v68, v68
	v_exp_f32_e32 v69, v69
	v_exp_f32_e32 v70, v70
	v_exp_f32_e32 v71, v71
	v_exp_f32_e32 v72, v72
	v_exp_f32_e32 v73, v73
	v_exp_f32_e32 v74, v74
	v_exp_f32_e32 v75, v75
	v_exp_f32_e32 v76, v76
	v_exp_f32_e32 v77, v77
	v_exp_f32_e32 v78, v78
	v_exp_f32_e32 v79, v79
	s_add_i32 s66, s59, 0xffff0000
	s_and_b32 s66, s66, 0x18000
	v_add_u32_e32 v248, s66, v188
	ds_read_b128 v[200:203], v248 offset:16384
	ds_read_b128 v[204:207], v248 offset:20480
	ds_read_b128 v[208:211], v248 offset:24576
	ds_read_b128 v[212:215], v248 offset:28672
	v_add_u32_e32 v249, s66, v187
	ds_read_b128 v[216:219], v249 offset:16384
	ds_read_b128 v[220:223], v249 offset:20480
	ds_read_b128 v[224:227], v249 offset:24576
	ds_read_b128 v[228:231], v249 offset:28672
.LBB0_384:
	s_waitcnt vmcnt(4)
	s_barrier
	s_add_i32 s65, s62, 0x104
	s_min_i32 s65, s65, s58
	s_add_i32 s66, s59, 0x8000
	s_and_b32 s66, s66, 0x18000
	s_add_i32 s85, s6, s66
	s_lshl_b32 s66, s65, 6
	s_ashr_i32 s67, s66, 31
	s_lshl_b64 s[86:87], s[66:67], 11
	s_add_u32 s86, s14, s86
	s_addc_u32 s87, s15, s87
	s_lshl_b64 s[66:67], s[66:67], 1
	s_add_i32 s65, s85, 0x2000
	s_add_u32 s66, s20, s66
	s_mov_b32 m0, s85
	s_addc_u32 s67, s21, s67
	s_add_i32 s88, s85, 0x4000
	global_load_lds_dwordx4 v162, s[86:87]
	s_mov_b32 m0, s65
	s_add_i32 s89, s85, 0x6000
	global_load_lds_dwordx4 v170, s[86:87]
	s_mov_b32 m0, s88
	s_nop 0
	global_load_lds_dwordx4 v166, s[66:67]
	s_mov_b32 m0, s89
	s_nop 0
	global_load_lds_dwordx4 v168, s[66:67]
	s_andn2_b64 vcc, exec, s[0:1]
	s_cbranch_vccnz .LBB0_386
	s_setprio 2
	s_add_i32 s0, s59, 0xffff0000
	s_and_b32 s0, s0, 0x18000
	v_add_u32_e32 v97, s0, v186
	ds_read_b128 v[98:101], v97 offset:16384
	ds_read_b128 v[102:105], v97 offset:20480
	ds_read_b128 v[106:109], v97 offset:24576
	ds_read_b128 v[110:113], v97 offset:28672
	s_add_i32 s67, s59, 0xffff8000
	s_and_b32 s67, s67, 0x18000
	v_cvt_pk_bf16_f32 v144, v80, v81
	v_cvt_pk_bf16_f32 v145, v82, v83
	v_cvt_pk_bf16_f32 v146, v84, v85
	v_cvt_pk_bf16_f32 v147, v86, v87
	v_add_f32_e32 v250, v81, v80
	v_add_f32_e32 v250, v82, v250
	s_waitcnt lgkmcnt(4)
	v_mfma_f32_32x32x16_bf16 v[48:63], v[200:203], v[144:147], v[48:63]
	v_cvt_pk_bf16_f32 v148, v88, v89
	v_add_f32_e32 v250, v83, v250
	v_add_f32_e32 v250, v84, v250
	v_add_u32_e32 v126, s0, v184
	ds_read_b128 v[114:117], v126 offset:16384
	ds_read_b128 v[118:121], v126 offset:20480
	ds_read_b128 v[122:125], v126 offset:24576
	ds_read_b128 v[196:199], v126 offset:28672
	v_mfma_f32_32x32x16_bf16 v[32:47], v[204:207], v[144:147], v[32:47]
	v_cvt_pk_bf16_f32 v149, v90, v91
	v_add_f32_e32 v250, v85, v250
	v_add_f32_e32 v250, v86, v250
	v_mfma_f32_32x32x16_bf16 v[16:31], v[208:211], v[144:147], v[16:31]
	v_cvt_pk_bf16_f32 v150, v92, v93
	v_add_f32_e32 v250, v87, v250
	v_add_f32_e32 v250, v88, v250
	v_mfma_f32_32x32x16_bf16 v[0:15], v[212:215], v[144:147], v[0:15]
	v_cvt_pk_bf16_f32 v151, v94, v95
	v_add_f32_e32 v250, v89, v250
	v_add_f32_e32 v250, v90, v250
	v_mfma_f32_32x32x16_bf16 v[48:63], v[216:219], v[148:151], v[48:63]
	v_cvt_pk_bf16_f32 v152, v64, v65
	v_add_f32_e32 v250, v91, v250
	v_add_f32_e32 v250, v92, v250
	v_mfma_f32_32x32x16_bf16 v[32:47], v[220:223], v[148:151], v[32:47]
	v_cvt_pk_bf16_f32 v153, v66, v67
	v_add_f32_e32 v250, v93, v250
	v_add_f32_e32 v250, v94, v250
	v_mfma_f32_32x32x16_bf16 v[16:31], v[224:227], v[148:151], v[16:31]
	v_cvt_pk_bf16_f32 v154, v68, v69
	v_add_f32_e32 v250, v95, v250
	v_add_f32_e32 v250, v64, v250
	v_mfma_f32_32x32x16_bf16 v[0:15], v[228:231], v[148:151], v[0:15]
	v_cvt_pk_bf16_f32 v155, v70, v71
	v_add_f32_e32 v250, v65, v250
	v_add_f32_e32 v250, v66, v250
	v_add_u32_e32 v97, s67, v177
	ds_read_b128 v[200:203], v97
	ds_read_b128 v[204:207], v97 offset:8192
	v_add_u32_e32 v126, s67, v178
	ds_read_b128 v[208:211], v126
	ds_read_b128 v[212:215], v126 offset:8192
	s_waitcnt lgkmcnt(8)
	v_mfma_f32_32x32x16_bf16 v[48:63], v[98:101], v[152:155], v[48:63]
	v_cvt_pk_bf16_f32 v156, v72, v73
	v_add_f32_e32 v250, v67, v250
	v_add_f32_e32 v250, v68, v250
	v_mfma_f32_32x32x16_bf16 v[32:47], v[102:105], v[152:155], v[32:47]
	v_cvt_pk_bf16_f32 v157, v74, v75
	v_add_f32_e32 v250, v69, v250
	v_add_f32_e32 v250, v70, v250
	v_mfma_f32_32x32x16_bf16 v[16:31], v[106:109], v[152:155], v[16:31]
	v_cvt_pk_bf16_f32 v158, v76, v77
	v_add_f32_e32 v250, v71, v250
	v_add_f32_e32 v250, v72, v250
	v_mfma_f32_32x32x16_bf16 v[0:15], v[110:113], v[152:155], v[0:15]
	v_cvt_pk_bf16_f32 v159, v78, v79
	v_add_f32_e32 v250, v73, v250
	v_add_f32_e32 v250, v74, v250
	v_add_u32_e32 v97, s67, v179
	ds_read_b128 v[216:219], v97
	ds_read_b128 v[220:223], v97 offset:8192
	v_add_u32_e32 v126, s67, v180
	ds_read_b128 v[224:227], v126
	ds_read_b128 v[228:231], v126 offset:8192
	s_waitcnt lgkmcnt(8)
	v_mfma_f32_32x32x16_bf16 v[48:63], v[114:117], v[156:159], v[48:63]
	v_add_f32_e32 v250, v75, v250
	v_add_f32_e32 v250, v76, v250
	v_mfma_f32_32x32x16_bf16 v[32:47], v[118:121], v[156:159], v[32:47]
	v_add_f32_e32 v250, v77, v250
	v_add_f32_e32 v250, v78, v250
	v_mfma_f32_32x32x16_bf16 v[16:31], v[122:125], v[156:159], v[16:31]
	v_add_f32_e32 v250, v79, v250
	v_mfma_f32_32x32x16_bf16 v[0:15], v[196:199], v[156:159], v[0:15]
	v_add_f32_e32 v181, v181, v250
	s_setprio 0
